# rmsnorm-modulate phases: per-sequence (1+scale) vector kept in registers across rows, only shift re-read per row (halves L2 traffic of the modulation vectors)
# speedup vs baseline: 1.0056x; 1.0056x over previous
; DI float bflo(unsigned w) { return __uint_as_float(w << 16); }
; DI float bfhi(unsigned w) { return __uint_as_float(w & 0xffff0000u); }
; #define MODSL ((const float*)WSP(WS_MODS) + (size_t)l * NSEQ * MODW)
; #define PMOD(T, ...) do { phase_mod<T>(__VA_ARGS__); phase_mod<T>(__VA_ARGS__); } while (0)
; #define PMOD(T, ...) phase_mod<T>(__VA_ARGS__)
; template <bool XI32>
; DI void phase_mod(const Frame& F, const void* xP, const void* xS, const float* g, const float* mods_l, int sidx, bool pool_out) {
;     bf16_t* U = (bf16_t*)(F.ws + WS_U);
;     for (int row = F.gw; row < NT; row += F.NGW) {
;         const int seq = seq_of_row(row);
;         f32x4 v[4]; float ss = 0.f;
;         if constexpr (XI32) { const float* xr = (const float*)(row < NP ? xP : xS) + (size_t)row * DM + 4 * F.lane;
; #pragma unroll
;             for (int j = 0; j < 4; ++j) v[j] = *(const f32x4*)(xr + 256 * j);
;         } else { const bf16_t* xr = (const bf16_t*)xP + (size_t)row * DM + 4 * F.lane;
; #pragma unroll
;             for (int j = 0; j < 4; ++j) { const u32x2 q = *(const u32x2*)(xr + 256 * j); v[j] = (f32x4){bflo(q.x), bfhi(q.x), bflo(q.y), bfhi(q.y)}; } }
; #pragma unroll
;         for (int j = 0; j < 4; ++j) ss += (v[j][0] * v[j][0] + v[j][1] * v[j][1]) + (v[j][2] * v[j][2] + v[j][3] * v[j][3]);
;         const float rstd = 1.f / sqrtf(wave_sum(ss) * (1.f / DM) + EPS);
;         const float* sh = mods_l + (size_t)seq * MODW + sidx * DM; const float* sc = sh + DM;
; __global__ void __launch_bounds__(512) fwd_megakernel(Params p) {
;     ...
;         if (l == 0) PMOD(true, F, F.in[0], F.in[1] - (size_t)NP * DM, NG, MODSL, 0, false); else PMOD(false, F, X_, X_, NG, MODSL, 0, false);
.LBB0_69:
	s_ashr_i32 s0, s0, 6
	v_readlane_b32 s1, v253, 2
	s_add_i32 s20, s0, s1
	s_cmp_lg_u32 s15, 0
	v_writelane_b32 v255, s15, 24
	s_cselect_b64 s[0:1], -1, 0
	v_writelane_b32 v255, s0, 25
	v_and_b32_e32 v1, 63, v1
	s_and_b64 vcc, exec, s[0:1]
	v_writelane_b32 v255, s1, 26
	s_mov_b64 s[0:1], -1
	s_cbranch_vccz .LBB0_74
	v_and_b32_e32 v2, 63, v220
	v_mov_b32_e32 v5, 0x23110
	v_mov_b32_e32 v6, 0x23058
	ds_read_b64 v[8:9], v5
	ds_read_b64 v[10:11], v6
	v_lshlrev_b32_e32 v3, 4, v2
	v_lshlrev_b32_e32 v2, 3, v2
	v_add_u32_e32 v4, 0x1000, v3
	v_readlane_b32 s45, v255, 24
	v_readlane_b32 s25, v253, 2
	v_readfirstlane_b32 s15, v220
	s_lshr_b32 s15, s15, 6
	s_add_i32 s15, s15, s25
	s_waitcnt lgkmcnt(0)
	v_readfirstlane_b32 s42, v8
	v_readfirstlane_b32 s43, v9
	v_readfirstlane_b32 s78, v10
	v_readfirstlane_b32 s79, v11
	s_mul_i32 s25, s45, 0x3000
	s_add_i32 s25, s25, 0
	s_add_u32 s78, s78, s25
	s_addc_u32 s79, s79, 0
	global_load_dwordx4 v[140:143], v3, s[78:79]
	global_load_dwordx4 v[144:147], v3, s[78:79] offset:1024
	global_load_dwordx4 v[148:151], v3, s[78:79] offset:2048
	global_load_dwordx4 v[152:155], v3, s[78:79] offset:3072
	s_mul_i32 s25, s45, 0x5a000
	s_add_i32 s25, s25, 1048576
	s_add_u32 s48, s42, s25
	s_addc_u32 s49, s43, 0
	s_lshl_b32 s25, s15, 11
	s_add_i32 s25, s25, 0xa400000
	s_add_u32 s92, s42, s25
	s_addc_u32 s93, s43, 0
	global_load_dwordx2 v[196:197], v2, s[92:93]
	global_load_dwordx2 v[198:199], v2, s[92:93] offset:512
	global_load_dwordx2 v[200:201], v2, s[92:93] offset:1024
	global_load_dwordx2 v[202:203], v2, s[92:93] offset:1536
	s_mov_b32 s45, -1
.Lpm_a_loop:
	s_lshr_b32 s25, s15, 13
	s_sub_i32 s32, s15, 0x4000
	s_lshr_b32 s32, s32, 5
	s_add_i32 s32, s32, 2
	s_cmp_lt_i32 s15, 0x4000
	s_cselect_b32 s25, s25, s32
	s_cmp_eq_u32 s25, s45
	s_cbranch_scc1 .Lpm_a_keep
	s_mov_b32 s45, s25
	s_mul_i32 s32, s25, 0x9000
	s_add_u32 s78, s48, s32
	s_addc_u32 s79, s49, 0
	global_load_dwordx4 v[156:159], v3, s[78:79]
	global_load_dwordx4 v[160:163], v3, s[78:79] offset:1024
	global_load_dwordx4 v[164:167], v3, s[78:79] offset:2048
	global_load_dwordx4 v[168:171], v3, s[78:79] offset:3072
	global_load_dwordx4 v[180:183], v4, s[78:79]
	global_load_dwordx4 v[184:187], v4, s[78:79] offset:1024
	global_load_dwordx4 v[188:191], v4, s[78:79] offset:2048
	global_load_dwordx4 v[192:195], v4, s[78:79] offset:3072
	s_waitcnt vmcnt(0)
	v_pk_add_f32 v[180:181], v[180:181], 1.0 op_sel_hi:[1,0]
	v_pk_add_f32 v[182:183], v[182:183], 1.0 op_sel_hi:[1,0]
	v_pk_add_f32 v[184:185], v[184:185], 1.0 op_sel_hi:[1,0]
	v_pk_add_f32 v[186:187], v[186:187], 1.0 op_sel_hi:[1,0]
	v_pk_add_f32 v[188:189], v[188:189], 1.0 op_sel_hi:[1,0]
	v_pk_add_f32 v[190:191], v[190:191], 1.0 op_sel_hi:[1,0]
	v_pk_add_f32 v[192:193], v[192:193], 1.0 op_sel_hi:[1,0]
	v_pk_add_f32 v[194:195], v[194:195], 1.0 op_sel_hi:[1,0]
	s_branch .Lpm_a_join
.Lpm_a_keep:
	global_load_dwordx4 v[156:159], v3, s[78:79]
	global_load_dwordx4 v[160:163], v3, s[78:79] offset:1024
	global_load_dwordx4 v[164:167], v3, s[78:79] offset:2048
	global_load_dwordx4 v[168:171], v3, s[78:79] offset:3072
	s_waitcnt vmcnt(4)
; DI unsigned cvt_pk_bf16(float lo, float hi) { unsigned r; asm volatile("v_cvt_pk_bf16_f32 %0, %1, %2" : "=v"(r) : "v"(lo), "v"(hi)); return r; }
; DI float bflo(unsigned w) { return __uint_as_float(w << 16); }
; DI float bfhi(unsigned w) { return __uint_as_float(w & 0xffff0000u); }
; template <bool XI32>
; DI void phase_mod(const Frame& F, const void* xP, const void* xS, const float* g, const float* mods_l, int sidx, bool pool_out) {
;     ...
;         f32x4 v[4]; float ss = 0.f;
;         if constexpr (XI32) { const float* xr = (const float*)(row < NP ? xP : xS) + (size_t)row * DM + 4 * F.lane;
; #pragma unroll
;             for (int j = 0; j < 4; ++j) v[j] = *(const f32x4*)(xr + 256 * j);
;         } else { const bf16_t* xr = (const bf16_t*)xP + (size_t)row * DM + 4 * F.lane;
; #pragma unroll
;             for (int j = 0; j < 4; ++j) { const u32x2 q = *(const u32x2*)(xr + 256 * j); v[j] = (f32x4){bflo(q.x), bfhi(q.x), bflo(q.y), bfhi(q.y)}; } }
; #pragma unroll
;         for (int j = 0; j < 4; ++j) ss += (v[j][0] * v[j][0] + v[j][1] * v[j][1]) + (v[j][2] * v[j][2] + v[j][3] * v[j][3]);
;         const float rstd = 1.f / sqrtf(wave_sum(ss) * (1.f / DM) + EPS);
;         const float* sh = mods_l + (size_t)seq * MODW + sidx * DM; const float* sc = sh + DM;
;         const int pos = pos_of_row(row); const int tl = row < NP ? SEQ : DSEQ;
;         float* po = nullptr;
;         if (pool_out && pos >= tl - 15) po = row < NP ? F.out + O_PP + ((size_t)seq * 15 + (pos - (tl - 15))) * DM : F.out + O_PS + ((size_t)(seq - 2) * 15 + (pos - (tl - 15))) * DM;
;         f32x4 g4v[4], s4v[4], c4v[4];
; #pragma unroll
;         for (int j = 0; j < 4; ++j) { const int col = 4 * F.lane + 256 * j; g4v[j] = *(const f32x4*)(g + col); s4v[j] = *(const f32x4*)(sh + col); c4v[j] = *(const f32x4*)(sc + col); }
; #pragma unroll
;         for (int j = 0; j < 4; ++j) { const int col = 4 * F.lane + 256 * j;
;             const f32x4 g4 = g4v[j], s4 = s4v[j], c4 = c4v[j];
;             const f32x4 y = (v[j] * rstd) * g4 * (1.f + c4) + s4;
;             u32x2 w; w.x = cvt_pk_bf16(y[0], y[1]); w.y = cvt_pk_bf16(y[2], y[3]);
;             *(u32x2*)(U + (size_t)row * DM + col) = w;
;             if (po) *(f32x4*)(po + col) = y; }
.Lpm_a_join:
	s_lshl_b32 s32, s15, 11
	s_add_i32 s32, s32, 0xe500000
	s_add_u32 s98, s42, s32
	s_addc_u32 s99, s43, 0
	s_add_i32 s41, s15, s94
	s_lshl_b32 s32, s41, 11
	s_add_i32 s32, s32, 0xa400000
	s_add_u32 s92, s42, s32
	s_addc_u32 s93, s43, 0
	v_lshlrev_b32_e32 v30, 16, v196
	v_and_b32_e32 v31, 0xffff0000, v196
	v_lshlrev_b32_e32 v32, 16, v197
	v_and_b32_e32 v33, 0xffff0000, v197
	v_lshlrev_b32_e32 v34, 16, v198
	v_and_b32_e32 v35, 0xffff0000, v198
	v_lshlrev_b32_e32 v36, 16, v199
	v_and_b32_e32 v37, 0xffff0000, v199
	v_lshlrev_b32_e32 v38, 16, v200
	v_and_b32_e32 v39, 0xffff0000, v200
	v_lshlrev_b32_e32 v40, 16, v201
	v_and_b32_e32 v41, 0xffff0000, v201
	v_lshlrev_b32_e32 v42, 16, v202
	v_and_b32_e32 v43, 0xffff0000, v202
	v_lshlrev_b32_e32 v44, 16, v203
	v_and_b32_e32 v45, 0xffff0000, v203
	global_load_dwordx2 v[196:197], v2, s[92:93]
	global_load_dwordx2 v[198:199], v2, s[92:93] offset:512
	global_load_dwordx2 v[200:201], v2, s[92:93] offset:1024
	global_load_dwordx2 v[202:203], v2, s[92:93] offset:1536
	v_mul_f32_e32 v5, v30, v30
	v_mul_f32_e32 v6, v31, v31
	v_mul_f32_e32 v7, v32, v32
	v_mul_f32_e32 v8, v33, v33
	v_fmac_f32_e32 v5, v34, v34
	v_fmac_f32_e32 v6, v35, v35
	v_fmac_f32_e32 v7, v36, v36
	v_fmac_f32_e32 v8, v37, v37
	v_fmac_f32_e32 v5, v38, v38
	v_fmac_f32_e32 v6, v39, v39
	v_fmac_f32_e32 v7, v40, v40
	v_fmac_f32_e32 v8, v41, v41
	v_fmac_f32_e32 v5, v42, v42
	v_fmac_f32_e32 v6, v43, v43
	v_fmac_f32_e32 v7, v44, v44
	v_fmac_f32_e32 v8, v45, v45
	v_add_f32_e32 v5, v5, v6
	v_add_f32_e32 v7, v7, v8
	v_add_f32_e32 v5, v5, v7
	s_nop 1
	v_add_f32_dpp v5, v5, v5 quad_perm:[1,0,3,2] row_mask:0xf bank_mask:0xf
	s_nop 1
	v_add_f32_dpp v5, v5, v5 quad_perm:[2,3,0,1] row_mask:0xf bank_mask:0xf
	s_nop 1
	v_add_f32_dpp v5, v5, v5 row_half_mirror row_mask:0xf bank_mask:0xf
	s_nop 1
	v_add_f32_dpp v5, v5, v5 row_mirror row_mask:0xf bank_mask:0xf
	s_nop 1
	v_readlane_b32 s25, v5, 0
	v_readlane_b32 s32, v5, 16
	v_readlane_b32 s66, v5, 32
	v_readlane_b32 s69, v5, 48
	v_mov_b32_e32 v7, 0x358637bd
	v_mov_b32_e32 v6, s25
	v_add_f32_e32 v6, s32, v6
	v_add_f32_e32 v6, s66, v6
	v_add_f32_e32 v6, s69, v6
	v_fmamk_f32 v6, v6, 0x3a800000, v7
	v_rsq_f32_e32 v58, v6
	s_nop 1
	v_pk_mul_f32 v[30:31], v[58:59], v[30:31] op_sel_hi:[0,1]
	v_pk_mul_f32 v[32:33], v[58:59], v[32:33] op_sel_hi:[0,1]
	v_pk_mul_f32 v[34:35], v[58:59], v[34:35] op_sel_hi:[0,1]
	v_pk_mul_f32 v[36:37], v[58:59], v[36:37] op_sel_hi:[0,1]
	v_pk_mul_f32 v[38:39], v[58:59], v[38:39] op_sel_hi:[0,1]
	v_pk_mul_f32 v[40:41], v[58:59], v[40:41] op_sel_hi:[0,1]
	v_pk_mul_f32 v[42:43], v[58:59], v[42:43] op_sel_hi:[0,1]
	v_pk_mul_f32 v[44:45], v[58:59], v[44:45] op_sel_hi:[0,1]
	v_pk_mul_f32 v[30:31], v[30:31], v[140:141]
	v_pk_mul_f32 v[32:33], v[32:33], v[142:143]
	v_pk_mul_f32 v[34:35], v[34:35], v[144:145]
	v_pk_mul_f32 v[36:37], v[36:37], v[146:147]
	v_pk_mul_f32 v[38:39], v[38:39], v[148:149]
	v_pk_mul_f32 v[40:41], v[40:41], v[150:151]
	v_pk_mul_f32 v[42:43], v[42:43], v[152:153]
	v_pk_mul_f32 v[44:45], v[44:45], v[154:155]
	v_pk_fma_f32 v[30:31], v[30:31], v[180:181], v[156:157]
	v_pk_fma_f32 v[32:33], v[32:33], v[182:183], v[158:159]
	v_pk_fma_f32 v[34:35], v[34:35], v[184:185], v[160:161]
	v_pk_fma_f32 v[36:37], v[36:37], v[186:187], v[162:163]
	v_pk_fma_f32 v[38:39], v[38:39], v[188:189], v[164:165]
	v_pk_fma_f32 v[40:41], v[40:41], v[190:191], v[166:167]
	v_pk_fma_f32 v[42:43], v[42:43], v[192:193], v[168:169]
	v_pk_fma_f32 v[44:45], v[44:45], v[194:195], v[170:171]
	v_cvt_pk_bf16_f32 v46, v30, v31
	v_cvt_pk_bf16_f32 v47, v32, v33
	v_cvt_pk_bf16_f32 v48, v34, v35
	v_cvt_pk_bf16_f32 v49, v36, v37
	v_cvt_pk_bf16_f32 v50, v38, v39
	v_cvt_pk_bf16_f32 v51, v40, v41
	v_cvt_pk_bf16_f32 v52, v42, v43
	v_cvt_pk_bf16_f32 v53, v44, v45
	global_store_dwordx2 v2, v[46:47], s[98:99]
	global_store_dwordx2 v2, v[48:49], s[98:99] offset:512
	global_store_dwordx2 v2, v[50:51], s[98:99] offset:1024
	global_store_dwordx2 v2, v[52:53], s[98:99] offset:1536
	s_mov_b32 s15, s41
	s_cmp_lt_i32 s15, 0x4100
	s_cbranch_scc1 .Lpm_a_loop

; DI float bflo(unsigned w) { return __uint_as_float(w << 16); }
; DI float bfhi(unsigned w) { return __uint_as_float(w & 0xffff0000u); }
; #define MODSL ((const float*)WSP(WS_MODS) + (size_t)l * NSEQ * MODW)
; #define PMOD(T, ...) do { phase_mod<T>(__VA_ARGS__); phase_mod<T>(__VA_ARGS__); } while (0)
; #define PMOD(T, ...) phase_mod<T>(__VA_ARGS__)
; template <bool XI32>
; DI void phase_mod(const Frame& F, const void* xP, const void* xS, const float* g, const float* mods_l, int sidx, bool pool_out) {
;     bf16_t* U = (bf16_t*)(F.ws + WS_U);
;     for (int row = F.gw; row < NT; row += F.NGW) {
;         const int seq = seq_of_row(row);
;         f32x4 v[4]; float ss = 0.f;
;         if constexpr (XI32) { const float* xr = (const float*)(row < NP ? xP : xS) + (size_t)row * DM + 4 * F.lane;
; #pragma unroll
;             for (int j = 0; j < 4; ++j) v[j] = *(const f32x4*)(xr + 256 * j);
;         } else { const bf16_t* xr = (const bf16_t*)xP + (size_t)row * DM + 4 * F.lane;
; #pragma unroll
;             for (int j = 0; j < 4; ++j) { const u32x2 q = *(const u32x2*)(xr + 256 * j); v[j] = (f32x4){bflo(q.x), bfhi(q.x), bflo(q.y), bfhi(q.y)}; } }
; #pragma unroll
;         for (int j = 0; j < 4; ++j) ss += (v[j][0] * v[j][0] + v[j][1] * v[j][1]) + (v[j][2] * v[j][2] + v[j][3] * v[j][3]);
;         const float rstd = 1.f / sqrtf(wave_sum(ss) * (1.f / DM) + EPS);
;         const float* sh = mods_l + (size_t)seq * MODW + sidx * DM; const float* sc = sh + DM;
;         const int pos = pos_of_row(row); const int tl = row < NP ? SEQ : DSEQ;
;         float* po = nullptr;
;         if (pool_out && pos >= tl - 15) po = row < NP ? F.out + O_PP + ((size_t)seq * 15 + (pos - (tl - 15))) * DM : F.out + O_PS + ((size_t)(seq - 2) * 15 + (pos - (tl - 15))) * DM;
; __global__ void __launch_bounds__(512) fwd_megakernel(Params p) {
;     ...
;         PMOD(false, F, X_, X_, NG + DM, MODSL, 3, kind == 1);
.LBB0_328:
	s_or_b64 exec, exec, s[20:21]
	v_readlane_b32 s0, v255, 32
	v_readlane_b32 s1, v255, 33
	s_and_b64 s[0:1], s[0:1], exec
	v_mov_b32_e32 v2, v220
	v_readlane_b32 s20, v255, 24
	s_waitcnt lgkmcnt(0)
	s_barrier
	s_cselect_b32 s24, 0, s20
	v_readfirstlane_b32 s0, v2
	s_ashr_i32 s0, s0, 6
	v_readlane_b32 s1, v253, 2
	s_add_i32 s26, s0, s1
	v_readlane_b32 s0, v254, 33
	v_readlane_b32 s2, v254, 34
	v_readlane_b32 s18, v254, 44
	v_mov_b32_e32 v1, s0
	ds_read_b64 v[4:5], v1
	v_mov_b32_e32 v1, s2
	s_mul_hi_u32 s21, s20, 0xc00
	s_mulk_i32 s20, 0xc00
	s_cmp_eq_u32 s24, 1
	s_waitcnt lgkmcnt(0)
	v_readfirstlane_b32 s0, v5
	v_readfirstlane_b32 s1, v4
	ds_read_b64 v[4:5], v1
	v_mov_b32_e32 v1, s18
	v_writelane_b32 v255, s20, 44
	s_cselect_b64 s[28:29], -1, 0
	s_cmp_lg_u32 s24, 1
	s_waitcnt lgkmcnt(0)
	v_readfirstlane_b32 s2, v5
	v_readfirstlane_b32 s15, v4
	ds_read_b64 v[4:5], v1
	v_writelane_b32 v255, s21, 45
	s_cselect_b64 s[20:21], -1, 0
	s_cmpk_gt_i32 s26, 0x40ff
	s_waitcnt lgkmcnt(0)
	v_readfirstlane_b32 s18, v5
	v_readfirstlane_b32 s19, v4
	s_cbranch_scc1 .LBB0_344
	v_and_b32_e32 v2, 63, v220
	v_mov_b32_e32 v5, 0x23110
	v_mov_b32_e32 v6, 0x23058
	ds_read_b64 v[8:9], v5
	ds_read_b64 v[10:11], v6
	v_lshlrev_b32_e32 v3, 4, v2
	v_lshlrev_b32_e32 v2, 3, v2
	v_add_u32_e32 v4, 0x1000, v3
	v_readlane_b32 s45, v255, 24
	v_readlane_b32 s25, v253, 2
	v_readfirstlane_b32 s15, v220
	s_lshr_b32 s15, s15, 6
	s_add_i32 s15, s15, s25
	s_waitcnt lgkmcnt(0)
	v_readfirstlane_b32 s42, v8
	v_readfirstlane_b32 s43, v9
	v_readfirstlane_b32 s78, v10
	v_readfirstlane_b32 s79, v11
	s_mul_i32 s25, s45, 0x3000
	s_add_i32 s25, s25, 4096
	s_add_u32 s78, s78, s25
	s_addc_u32 s79, s79, 0
	global_load_dwordx4 v[140:143], v3, s[78:79]
	global_load_dwordx4 v[144:147], v3, s[78:79] offset:1024
	global_load_dwordx4 v[148:151], v3, s[78:79] offset:2048
	global_load_dwordx4 v[152:155], v3, s[78:79] offset:3072
	s_mul_i32 s25, s45, 0x5a000
	s_add_i32 s25, s25, 1060864
	s_add_u32 s48, s42, s25
	s_addc_u32 s49, s43, 0
	s_lshl_b32 s25, s15, 11
	s_add_i32 s25, s25, 0xa400000
	s_add_u32 s92, s42, s25
	s_addc_u32 s93, s43, 0
	global_load_dwordx2 v[196:197], v2, s[92:93]
	global_load_dwordx2 v[198:199], v2, s[92:93] offset:512
	global_load_dwordx2 v[200:201], v2, s[92:93] offset:1024
	global_load_dwordx2 v[202:203], v2, s[92:93] offset:1536
	s_mov_b32 s45, -1

; DI unsigned cvt_pk_bf16(float lo, float hi) { unsigned r; asm volatile("v_cvt_pk_bf16_f32 %0, %1, %2" : "=v"(r) : "v"(lo), "v"(hi)); return r; }
; DI float bflo(unsigned w) { return __uint_as_float(w << 16); }
; DI float bfhi(unsigned w) { return __uint_as_float(w & 0xffff0000u); }
; template <bool XI32>
; DI void phase_mod(const Frame& F, const void* xP, const void* xS, const float* g, const float* mods_l, int sidx, bool pool_out) {
;     ...
;         f32x4 v[4]; float ss = 0.f;
;         if constexpr (XI32) { const float* xr = (const float*)(row < NP ? xP : xS) + (size_t)row * DM + 4 * F.lane;
; #pragma unroll
;             for (int j = 0; j < 4; ++j) v[j] = *(const f32x4*)(xr + 256 * j);
;         } else { const bf16_t* xr = (const bf16_t*)xP + (size_t)row * DM + 4 * F.lane;
; #pragma unroll
;             for (int j = 0; j < 4; ++j) { const u32x2 q = *(const u32x2*)(xr + 256 * j); v[j] = (f32x4){bflo(q.x), bfhi(q.x), bflo(q.y), bfhi(q.y)}; } }
; #pragma unroll
;         for (int j = 0; j < 4; ++j) ss += (v[j][0] * v[j][0] + v[j][1] * v[j][1]) + (v[j][2] * v[j][2] + v[j][3] * v[j][3]);
;         const float rstd = 1.f / sqrtf(wave_sum(ss) * (1.f / DM) + EPS);
;         const float* sh = mods_l + (size_t)seq * MODW + sidx * DM; const float* sc = sh + DM;
;         const int pos = pos_of_row(row); const int tl = row < NP ? SEQ : DSEQ;
;         float* po = nullptr;
;         if (pool_out && pos >= tl - 15) po = row < NP ? F.out + O_PP + ((size_t)seq * 15 + (pos - (tl - 15))) * DM : F.out + O_PS + ((size_t)(seq - 2) * 15 + (pos - (tl - 15))) * DM;
;         f32x4 g4v[4], s4v[4], c4v[4];
; #pragma unroll
;         for (int j = 0; j < 4; ++j) { const int col = 4 * F.lane + 256 * j; g4v[j] = *(const f32x4*)(g + col); s4v[j] = *(const f32x4*)(sh + col); c4v[j] = *(const f32x4*)(sc + col); }
; #pragma unroll
;         for (int j = 0; j < 4; ++j) { const int col = 4 * F.lane + 256 * j;
;             const f32x4 g4 = g4v[j], s4 = s4v[j], c4 = c4v[j];
;             const f32x4 y = (v[j] * rstd) * g4 * (1.f + c4) + s4;
;             u32x2 w; w.x = cvt_pk_bf16(y[0], y[1]); w.y = cvt_pk_bf16(y[2], y[3]);
;             *(u32x2*)(U + (size_t)row * DM + col) = w;
;             if (po) *(f32x4*)(po + col) = y; }
.Lpm_b_join:
	s_lshl_b32 s32, s15, 11
	s_add_i32 s32, s32, 0xe500000
	s_add_u32 s98, s42, s32
	s_addc_u32 s99, s43, 0
	s_add_i32 s41, s15, s94
	s_lshl_b32 s32, s41, 11
	s_add_i32 s32, s32, 0xa400000
	s_add_u32 s92, s42, s32
	s_addc_u32 s93, s43, 0
	v_lshlrev_b32_e32 v30, 16, v196
	v_and_b32_e32 v31, 0xffff0000, v196
	v_lshlrev_b32_e32 v32, 16, v197
	v_and_b32_e32 v33, 0xffff0000, v197
	v_lshlrev_b32_e32 v34, 16, v198
	v_and_b32_e32 v35, 0xffff0000, v198
	v_lshlrev_b32_e32 v36, 16, v199
	v_and_b32_e32 v37, 0xffff0000, v199
	v_lshlrev_b32_e32 v38, 16, v200
	v_and_b32_e32 v39, 0xffff0000, v200
	v_lshlrev_b32_e32 v40, 16, v201
	v_and_b32_e32 v41, 0xffff0000, v201
	v_lshlrev_b32_e32 v42, 16, v202
	v_and_b32_e32 v43, 0xffff0000, v202
	v_lshlrev_b32_e32 v44, 16, v203
	v_and_b32_e32 v45, 0xffff0000, v203
	global_load_dwordx2 v[196:197], v2, s[92:93]
	global_load_dwordx2 v[198:199], v2, s[92:93] offset:512
	global_load_dwordx2 v[200:201], v2, s[92:93] offset:1024
	global_load_dwordx2 v[202:203], v2, s[92:93] offset:1536
	v_mul_f32_e32 v5, v30, v30
	v_mul_f32_e32 v6, v31, v31
	v_mul_f32_e32 v7, v32, v32
	v_mul_f32_e32 v8, v33, v33
	v_fmac_f32_e32 v5, v34, v34
	v_fmac_f32_e32 v6, v35, v35
	v_fmac_f32_e32 v7, v36, v36
	v_fmac_f32_e32 v8, v37, v37
	v_fmac_f32_e32 v5, v38, v38
	v_fmac_f32_e32 v6, v39, v39
	v_fmac_f32_e32 v7, v40, v40
	v_fmac_f32_e32 v8, v41, v41
	v_fmac_f32_e32 v5, v42, v42
	v_fmac_f32_e32 v6, v43, v43
	v_fmac_f32_e32 v7, v44, v44
	v_fmac_f32_e32 v8, v45, v45
	v_add_f32_e32 v5, v5, v6
	v_add_f32_e32 v7, v7, v8
	v_add_f32_e32 v5, v5, v7
	s_nop 1
	v_add_f32_dpp v5, v5, v5 quad_perm:[1,0,3,2] row_mask:0xf bank_mask:0xf
	s_nop 1
	v_add_f32_dpp v5, v5, v5 quad_perm:[2,3,0,1] row_mask:0xf bank_mask:0xf
	s_nop 1
	v_add_f32_dpp v5, v5, v5 row_half_mirror row_mask:0xf bank_mask:0xf
	s_nop 1
	v_add_f32_dpp v5, v5, v5 row_mirror row_mask:0xf bank_mask:0xf
	s_nop 1
	v_readlane_b32 s25, v5, 0
	v_readlane_b32 s32, v5, 16
	v_readlane_b32 s66, v5, 32
	v_readlane_b32 s69, v5, 48
	v_mov_b32_e32 v7, 0x358637bd
	v_mov_b32_e32 v6, s25
	v_add_f32_e32 v6, s32, v6
	v_add_f32_e32 v6, s66, v6
	v_add_f32_e32 v6, s69, v6
	v_fmamk_f32 v6, v6, 0x3a800000, v7
	v_rsq_f32_e32 v58, v6
	s_nop 1
	v_pk_mul_f32 v[30:31], v[58:59], v[30:31] op_sel_hi:[0,1]
	v_pk_mul_f32 v[32:33], v[58:59], v[32:33] op_sel_hi:[0,1]
	v_pk_mul_f32 v[34:35], v[58:59], v[34:35] op_sel_hi:[0,1]
	v_pk_mul_f32 v[36:37], v[58:59], v[36:37] op_sel_hi:[0,1]
	v_pk_mul_f32 v[38:39], v[58:59], v[38:39] op_sel_hi:[0,1]
	v_pk_mul_f32 v[40:41], v[58:59], v[40:41] op_sel_hi:[0,1]
	v_pk_mul_f32 v[42:43], v[58:59], v[42:43] op_sel_hi:[0,1]
	v_pk_mul_f32 v[44:45], v[58:59], v[44:45] op_sel_hi:[0,1]
	v_pk_mul_f32 v[30:31], v[30:31], v[140:141]
	v_pk_mul_f32 v[32:33], v[32:33], v[142:143]
	v_pk_mul_f32 v[34:35], v[34:35], v[144:145]
	v_pk_mul_f32 v[36:37], v[36:37], v[146:147]
	v_pk_mul_f32 v[38:39], v[38:39], v[148:149]
	v_pk_mul_f32 v[40:41], v[40:41], v[150:151]
	v_pk_mul_f32 v[42:43], v[42:43], v[152:153]
	v_pk_mul_f32 v[44:45], v[44:45], v[154:155]
	v_pk_fma_f32 v[30:31], v[30:31], v[180:181], v[156:157]
	v_pk_fma_f32 v[32:33], v[32:33], v[182:183], v[158:159]
	v_pk_fma_f32 v[34:35], v[34:35], v[184:185], v[160:161]
	v_pk_fma_f32 v[36:37], v[36:37], v[186:187], v[162:163]
	v_pk_fma_f32 v[38:39], v[38:39], v[188:189], v[164:165]
	v_pk_fma_f32 v[40:41], v[40:41], v[190:191], v[166:167]
	v_pk_fma_f32 v[42:43], v[42:43], v[192:193], v[168:169]
	v_pk_fma_f32 v[44:45], v[44:45], v[194:195], v[170:171]
	v_cvt_pk_bf16_f32 v46, v30, v31
	v_cvt_pk_bf16_f32 v47, v32, v33
	v_cvt_pk_bf16_f32 v48, v34, v35
	v_cvt_pk_bf16_f32 v49, v36, v37
	v_cvt_pk_bf16_f32 v50, v38, v39
	v_cvt_pk_bf16_f32 v51, v40, v41
	v_cvt_pk_bf16_f32 v52, v42, v43
	v_cvt_pk_bf16_f32 v53, v44, v45
	global_store_dwordx2 v2, v[46:47], s[98:99]
	global_store_dwordx2 v2, v[48:49], s[98:99] offset:512
	global_store_dwordx2 v2, v[50:51], s[98:99] offset:1024
	global_store_dwordx2 v2, v[52:53], s[98:99] offset:1536
	s_cmp_lg_u32 s24, 1
	s_cbranch_scc1 .Lpm_b_nopool
	s_cmp_lt_i32 s15, 0x4000
	s_cbranch_scc0 .Lpm_b_pool_s
	s_and_b32 s32, s15, 0x1fff
	s_cmp_lt_u32 s32, 0x1ff1
	s_cbranch_scc1 .Lpm_b_nopool
	s_lshr_b32 s66, s15, 13
	s_mul_i32 s66, s66, 15
	s_add_i32 s66, s66, s32
	s_sub_i32 s66, s66, 0x1ff1
	s_lshl_b32 s66, s66, 12
	s_add_i32 s66, s66, 0x4164000
	s_branch .Lpm_b_pool_st

; DI float bflo(unsigned w) { return __uint_as_float(w << 16); }
; DI float bfhi(unsigned w) { return __uint_as_float(w & 0xffff0000u); }
; #define MODSL ((const float*)WSP(WS_MODS) + (size_t)l * NSEQ * MODW)
; #define PMOD(T, ...) do { phase_mod<T>(__VA_ARGS__); phase_mod<T>(__VA_ARGS__); } while (0)
; #define PMOD(T, ...) phase_mod<T>(__VA_ARGS__)
; template <bool XI32>
; DI void phase_mod(const Frame& F, const void* xP, const void* xS, const float* g, const float* mods_l, int sidx, bool pool_out) {
;     bf16_t* U = (bf16_t*)(F.ws + WS_U);
;     for (int row = F.gw; row < NT; row += F.NGW) {
;         const int seq = seq_of_row(row);
;         f32x4 v[4]; float ss = 0.f;
;         if constexpr (XI32) { const float* xr = (const float*)(row < NP ? xP : xS) + (size_t)row * DM + 4 * F.lane;
; #pragma unroll
;             for (int j = 0; j < 4; ++j) v[j] = *(const f32x4*)(xr + 256 * j);
;         } else { const bf16_t* xr = (const bf16_t*)xP + (size_t)row * DM + 4 * F.lane;
; #pragma unroll
;             for (int j = 0; j < 4; ++j) { const u32x2 q = *(const u32x2*)(xr + 256 * j); v[j] = (f32x4){bflo(q.x), bfhi(q.x), bflo(q.y), bfhi(q.y)}; } }
; #pragma unroll
;         for (int j = 0; j < 4; ++j) ss += (v[j][0] * v[j][0] + v[j][1] * v[j][1]) + (v[j][2] * v[j][2] + v[j][3] * v[j][3]);
;         const float rstd = 1.f / sqrtf(wave_sum(ss) * (1.f / DM) + EPS);
;         const float* sh = mods_l + (size_t)seq * MODW + sidx * DM; const float* sc = sh + DM;
; __global__ void __launch_bounds__(512) fwd_megakernel(Params p) {
;     ...
;         PMOD(false, F, X_, X_, NG + 2 * DM, MODSL, 6, false);
.LBB0_2102:
	s_or_b64 exec, exec, s[0:1]
	v_mov_b32_e32 v2, v220
	s_waitcnt lgkmcnt(0)
	s_barrier
	v_readlane_b32 s1, v253, 2
	v_readfirstlane_b32 s0, v2
	s_ashr_i32 s0, s0, 6
	s_add_i32 s20, s0, s1
	v_readlane_b32 s0, v254, 33
	v_readlane_b32 s2, v254, 44
	s_cmpk_gt_i32 s20, 0x40ff
	v_mov_b32_e32 v1, s0
	v_readlane_b32 s0, v254, 34
	ds_read_b64 v[4:5], v1
	s_movk_i32 s84, 0x5000
	v_mov_b32_e32 v1, s0
	s_waitcnt lgkmcnt(0)
	ds_read_b64 v[4:5], v1
	v_mov_b32_e32 v1, s2
	s_waitcnt lgkmcnt(0)
	v_readfirstlane_b32 s0, v5
	v_readfirstlane_b32 s1, v4
	ds_read_b64 v[4:5], v1
	s_waitcnt lgkmcnt(0)
	v_readfirstlane_b32 s2, v5
	v_readfirstlane_b32 s15, v4
	s_cbranch_scc1 .LBB0_2105
	v_and_b32_e32 v2, 63, v220
	v_mov_b32_e32 v5, 0x23110
	v_mov_b32_e32 v6, 0x23058
	ds_read_b64 v[8:9], v5
	ds_read_b64 v[10:11], v6
	v_lshlrev_b32_e32 v3, 4, v2
	v_lshlrev_b32_e32 v2, 3, v2
	v_add_u32_e32 v4, 0x1000, v3
	v_readlane_b32 s45, v255, 24
	v_readlane_b32 s25, v253, 2
	v_readfirstlane_b32 s15, v220
	s_lshr_b32 s15, s15, 6
	s_add_i32 s15, s15, s25
	s_waitcnt lgkmcnt(0)
	v_readfirstlane_b32 s42, v8
	v_readfirstlane_b32 s43, v9
	v_readfirstlane_b32 s78, v10
	v_readfirstlane_b32 s79, v11
	s_mul_i32 s25, s45, 0x3000
	s_add_i32 s25, s25, 8192
	s_add_u32 s78, s78, s25
	s_addc_u32 s79, s79, 0
	global_load_dwordx4 v[140:143], v3, s[78:79]
	global_load_dwordx4 v[144:147], v3, s[78:79] offset:1024
	global_load_dwordx4 v[148:151], v3, s[78:79] offset:2048
	global_load_dwordx4 v[152:155], v3, s[78:79] offset:3072
	s_mul_i32 s25, s45, 0x5a000
	s_add_i32 s25, s25, 1073152
	s_add_u32 s48, s42, s25
	s_addc_u32 s49, s43, 0
	s_lshl_b32 s25, s15, 11
	s_add_i32 s25, s25, 0xa400000
	s_add_u32 s92, s42, s25
	s_addc_u32 s93, s43, 0
	global_load_dwordx2 v[196:197], v2, s[92:93]
	global_load_dwordx2 v[198:199], v2, s[92:93] offset:512
	global_load_dwordx2 v[200:201], v2, s[92:93] offset:1024
	global_load_dwordx2 v[202:203], v2, s[92:93] offset:1536
	s_mov_b32 s45, -1
